# NSA top-16 rank loop bounded by the causal block index qb (lanes > qb hold score -1 and contribute nothing): identical masks, half the iterations
# speedup vs baseline: 1.0119x; 1.0064x over previous
.LBB0_308:
	s_or_b64 exec, exec, s[0:1]
	s_waitcnt lgkmcnt(0)
	ds_read_b32 v0, v206 offset:36864
	v_cmp_eq_u32_e32 vcc, s67, v168
	s_or_b64 s[0:1], s[6:7], vcc
	v_cmp_eq_u32_e32 vcc, s67, v207
	s_or_b64 vcc, s[0:1], vcc
	v_cmp_lt_i32_e64 s[8:9], s67, v168
	s_waitcnt lgkmcnt(0)
	v_cndmask_b32_e32 v0, v0, v231, vcc
	s_mov_b32 s18, 0
	v_cndmask_b32_e64 v0, v0, -1.0, s[8:9]
	v_mov_b32_e32 v34, 0
	s_add_i32 s101, s67, 4
	s_and_b32 s101, s101, 0x7c
.LBB0_309:
	v_readlane_b32 s10, v0, s18
	v_cmp_lt_u32_e64 s[12:13], s18, v168
	s_nop 0
	v_cmp_gt_f32_e64 s[0:1], s10, v0
	v_cmp_eq_f32_e64 s[10:11], s10, v0
	s_and_b64 s[10:11], s[10:11], s[12:13]
	s_add_i32 s12, s18, 1
	s_or_b64 s[0:1], s[0:1], s[10:11]
	v_readlane_b32 s10, v0, s12
	v_cndmask_b32_e64 v35, 0, 1, s[0:1]
	v_cmp_lt_u32_e64 s[12:13], s12, v168
	v_cmp_gt_f32_e64 s[0:1], s10, v0
	v_cmp_eq_f32_e64 s[10:11], s10, v0
	s_and_b64 s[10:11], s[10:11], s[12:13]
	s_or_b64 s[0:1], s[0:1], s[10:11]
	s_add_i32 s12, s18, 2
	v_addc_co_u32_e64 v34, s[0:1], v34, v35, s[0:1]
	v_readlane_b32 s10, v0, s12
	v_cmp_lt_u32_e64 s[12:13], s12, v168
	s_nop 0
	v_cmp_gt_f32_e64 s[0:1], s10, v0
	v_cmp_eq_f32_e64 s[10:11], s10, v0
	s_and_b64 s[10:11], s[10:11], s[12:13]
	s_add_i32 s12, s18, 3
	s_or_b64 s[0:1], s[0:1], s[10:11]
	v_readlane_b32 s10, v0, s12
	v_cndmask_b32_e64 v35, 0, 1, s[0:1]
	v_cmp_lt_u32_e64 s[12:13], s12, v168
	v_cmp_gt_f32_e64 s[0:1], s10, v0
	v_cmp_eq_f32_e64 s[10:11], s10, v0
	s_and_b64 s[10:11], s[10:11], s[12:13]
	s_or_b64 s[0:1], s[0:1], s[10:11]
	s_add_i32 s18, s18, 4
	v_addc_co_u32_e64 v34, s[0:1], v34, v35, s[0:1]
	s_cmp_lt_u32 s18, s101
	s_cbranch_scc1 .LBB0_309
	v_cmp_gt_u32_e64 s[0:1], 16, v34
	v_cmp_le_f32_e64 s[10:11], 0, v0
	s_and_b64 s[0:1], s[0:1], s[10:11]
	v_cndmask_b32_e64 v0, 0, 1, s[0:1]
	v_cmp_ne_u32_e64 s[20:21], 0, v0
	s_and_saveexec_b64 s[0:1], s[6:7]
	v_mov_b32_e32 v0, s70
	v_mov_b64_e32 v[34:35], s[20:21]
	ds_write_b64 v0, v[34:35] offset:53248
	s_or_b64 exec, exec, s[0:1]
	ds_read_b32 v0, v206 offset:37120
	s_mov_b32 s18, 0
	v_mov_b32_e32 v34, 0
	s_waitcnt lgkmcnt(0)
	v_cndmask_b32_e32 v0, v0, v231, vcc
	v_cndmask_b32_e64 v0, v0, -1.0, s[8:9]
.LBB0_313:
	s_nop 0
	v_readlane_b32 s10, v0, s18
	v_cmp_lt_u32_e64 s[12:13], s18, v168
	s_nop 0
	v_cmp_gt_f32_e64 s[0:1], s10, v0
	v_cmp_eq_f32_e64 s[10:11], s10, v0
	s_and_b64 s[10:11], s[10:11], s[12:13]
	s_add_i32 s12, s18, 1
	s_or_b64 s[0:1], s[0:1], s[10:11]
	v_readlane_b32 s10, v0, s12
	v_cndmask_b32_e64 v35, 0, 1, s[0:1]
	v_cmp_lt_u32_e64 s[12:13], s12, v168
	v_cmp_gt_f32_e64 s[0:1], s10, v0
	v_cmp_eq_f32_e64 s[10:11], s10, v0
	s_and_b64 s[10:11], s[10:11], s[12:13]
	s_or_b64 s[0:1], s[0:1], s[10:11]
	s_add_i32 s12, s18, 2
	v_addc_co_u32_e64 v34, s[0:1], v34, v35, s[0:1]
	v_readlane_b32 s10, v0, s12
	v_cmp_lt_u32_e64 s[12:13], s12, v168
	s_nop 0
	v_cmp_gt_f32_e64 s[0:1], s10, v0
	v_cmp_eq_f32_e64 s[10:11], s10, v0
	s_and_b64 s[10:11], s[10:11], s[12:13]
	s_add_i32 s12, s18, 3
	s_or_b64 s[0:1], s[0:1], s[10:11]
	v_readlane_b32 s10, v0, s12
	v_cndmask_b32_e64 v35, 0, 1, s[0:1]
	v_cmp_lt_u32_e64 s[12:13], s12, v168
	v_cmp_gt_f32_e64 s[0:1], s10, v0
	v_cmp_eq_f32_e64 s[10:11], s10, v0
	s_and_b64 s[10:11], s[10:11], s[12:13]
	s_or_b64 s[0:1], s[0:1], s[10:11]
	s_add_i32 s18, s18, 4
	v_addc_co_u32_e64 v34, s[0:1], v34, v35, s[0:1]
	s_cmp_lt_u32 s18, s101
	s_cbranch_scc1 .LBB0_313
	v_cmp_gt_u32_e64 s[0:1], 16, v34
	v_cmp_le_f32_e64 s[10:11], 0, v0
	s_and_b64 s[0:1], s[0:1], s[10:11]
	v_cndmask_b32_e64 v0, 0, 1, s[0:1]
	v_cmp_ne_u32_e64 s[86:87], 0, v0
	s_and_saveexec_b64 s[0:1], s[6:7]
	v_mov_b32_e32 v0, s70
	v_mov_b64_e32 v[34:35], s[86:87]
	ds_write_b64 v0, v[34:35] offset:53256
	s_or_b64 exec, exec, s[0:1]
	ds_read_b32 v0, v206 offset:37376
	s_mov_b32 s18, 0
	v_mov_b32_e32 v34, 0
	s_waitcnt lgkmcnt(0)
	v_cndmask_b32_e32 v0, v0, v231, vcc
	v_cndmask_b32_e64 v0, v0, -1.0, s[8:9]
.LBB0_317:
	s_nop 0
	v_readlane_b32 s10, v0, s18
	v_cmp_lt_u32_e64 s[12:13], s18, v168
	s_nop 0
	v_cmp_gt_f32_e64 s[0:1], s10, v0
	v_cmp_eq_f32_e64 s[10:11], s10, v0
	s_and_b64 s[10:11], s[10:11], s[12:13]
	s_add_i32 s12, s18, 1
	s_or_b64 s[0:1], s[0:1], s[10:11]
	v_readlane_b32 s10, v0, s12
	v_cndmask_b32_e64 v35, 0, 1, s[0:1]
	v_cmp_lt_u32_e64 s[12:13], s12, v168
	v_cmp_gt_f32_e64 s[0:1], s10, v0
	v_cmp_eq_f32_e64 s[10:11], s10, v0
	s_and_b64 s[10:11], s[10:11], s[12:13]
	s_or_b64 s[0:1], s[0:1], s[10:11]
	s_add_i32 s12, s18, 2
	v_addc_co_u32_e64 v34, s[0:1], v34, v35, s[0:1]
	v_readlane_b32 s10, v0, s12
	v_cmp_lt_u32_e64 s[12:13], s12, v168
	s_nop 0
	v_cmp_gt_f32_e64 s[0:1], s10, v0
	v_cmp_eq_f32_e64 s[10:11], s10, v0
	s_and_b64 s[10:11], s[10:11], s[12:13]
	s_add_i32 s12, s18, 3
	s_or_b64 s[0:1], s[0:1], s[10:11]
	v_readlane_b32 s10, v0, s12
	v_cndmask_b32_e64 v35, 0, 1, s[0:1]
	v_cmp_lt_u32_e64 s[12:13], s12, v168
	v_cmp_gt_f32_e64 s[0:1], s10, v0
	v_cmp_eq_f32_e64 s[10:11], s10, v0
	s_and_b64 s[10:11], s[10:11], s[12:13]
	s_or_b64 s[0:1], s[0:1], s[10:11]
	s_add_i32 s18, s18, 4
	v_addc_co_u32_e64 v34, s[0:1], v34, v35, s[0:1]
	s_cmp_lt_u32 s18, s101
	s_cbranch_scc1 .LBB0_317
	v_cmp_gt_u32_e64 s[0:1], 16, v34
	v_cmp_le_f32_e64 s[10:11], 0, v0
	s_and_b64 s[0:1], s[0:1], s[10:11]
	v_cndmask_b32_e64 v0, 0, 1, s[0:1]
	v_cmp_ne_u32_e64 s[24:25], 0, v0
	s_and_saveexec_b64 s[0:1], s[6:7]
	v_mov_b32_e32 v0, s70
	v_mov_b64_e32 v[34:35], s[24:25]
	ds_write_b64 v0, v[34:35] offset:53264
	s_or_b64 exec, exec, s[0:1]
	ds_read_b32 v0, v206 offset:37632
	s_mov_b32 s18, 0
	v_mov_b32_e32 v34, 0
	s_waitcnt lgkmcnt(0)
	v_cndmask_b32_e32 v0, v0, v231, vcc
	v_cndmask_b32_e64 v0, v0, -1.0, s[8:9]
.LBB0_321:
	s_nop 0
	v_readlane_b32 s10, v0, s18
	v_cmp_lt_u32_e64 s[12:13], s18, v168
	s_nop 0
	v_cmp_gt_f32_e64 s[0:1], s10, v0
	v_cmp_eq_f32_e64 s[10:11], s10, v0
	s_and_b64 s[10:11], s[10:11], s[12:13]
	s_add_i32 s12, s18, 1
	s_or_b64 s[0:1], s[0:1], s[10:11]
	v_readlane_b32 s10, v0, s12
	v_cndmask_b32_e64 v35, 0, 1, s[0:1]
	v_cmp_lt_u32_e64 s[12:13], s12, v168
	v_cmp_gt_f32_e64 s[0:1], s10, v0
	v_cmp_eq_f32_e64 s[10:11], s10, v0
	s_and_b64 s[10:11], s[10:11], s[12:13]
	s_or_b64 s[0:1], s[0:1], s[10:11]
	s_add_i32 s12, s18, 2
	v_addc_co_u32_e64 v34, s[0:1], v34, v35, s[0:1]
	v_readlane_b32 s10, v0, s12
	v_cmp_lt_u32_e64 s[12:13], s12, v168
	s_nop 0
	v_cmp_gt_f32_e64 s[0:1], s10, v0
	v_cmp_eq_f32_e64 s[10:11], s10, v0
	s_and_b64 s[10:11], s[10:11], s[12:13]
	s_add_i32 s12, s18, 3
	s_or_b64 s[0:1], s[0:1], s[10:11]
	v_readlane_b32 s10, v0, s12
	v_cndmask_b32_e64 v35, 0, 1, s[0:1]
	v_cmp_lt_u32_e64 s[12:13], s12, v168
	v_cmp_gt_f32_e64 s[0:1], s10, v0
	v_cmp_eq_f32_e64 s[10:11], s10, v0
	s_and_b64 s[10:11], s[10:11], s[12:13]
	s_or_b64 s[0:1], s[0:1], s[10:11]
	s_add_i32 s18, s18, 4
	v_addc_co_u32_e64 v34, s[0:1], v34, v35, s[0:1]
	s_cmp_lt_u32 s18, s101
	s_cbranch_scc1 .LBB0_321
	v_cmp_gt_u32_e64 s[0:1], 16, v34
	v_cmp_le_f32_e64 s[10:11], 0, v0
	s_and_b64 s[0:1], s[0:1], s[10:11]
	v_cndmask_b32_e64 v0, 0, 1, s[0:1]
	v_cmp_ne_u32_e64 s[26:27], 0, v0
	s_and_saveexec_b64 s[0:1], s[6:7]
	v_mov_b32_e32 v0, s70
	v_mov_b64_e32 v[34:35], s[26:27]
	ds_write_b64 v0, v[34:35] offset:53272
	s_or_b64 exec, exec, s[0:1]
	ds_read_b32 v0, v206 offset:37888
	s_mov_b32 s18, 0
	v_mov_b32_e32 v34, 0
	s_waitcnt lgkmcnt(0)
	v_cndmask_b32_e32 v0, v0, v231, vcc
	v_cndmask_b32_e64 v0, v0, -1.0, s[8:9]
.LBB0_325:
	s_nop 0
	v_readlane_b32 s10, v0, s18
	v_cmp_lt_u32_e64 s[12:13], s18, v168
	s_nop 0
	v_cmp_gt_f32_e64 s[0:1], s10, v0
	v_cmp_eq_f32_e64 s[10:11], s10, v0
	s_and_b64 s[10:11], s[10:11], s[12:13]
	s_add_i32 s12, s18, 1
	s_or_b64 s[0:1], s[0:1], s[10:11]
	v_readlane_b32 s10, v0, s12
	v_cndmask_b32_e64 v35, 0, 1, s[0:1]
	v_cmp_lt_u32_e64 s[12:13], s12, v168
	v_cmp_gt_f32_e64 s[0:1], s10, v0
	v_cmp_eq_f32_e64 s[10:11], s10, v0
	s_and_b64 s[10:11], s[10:11], s[12:13]
	s_or_b64 s[0:1], s[0:1], s[10:11]
	s_add_i32 s12, s18, 2
	v_addc_co_u32_e64 v34, s[0:1], v34, v35, s[0:1]
	v_readlane_b32 s10, v0, s12
	v_cmp_lt_u32_e64 s[12:13], s12, v168
	s_nop 0
	v_cmp_gt_f32_e64 s[0:1], s10, v0
	v_cmp_eq_f32_e64 s[10:11], s10, v0
	s_and_b64 s[10:11], s[10:11], s[12:13]
	s_add_i32 s12, s18, 3
	s_or_b64 s[0:1], s[0:1], s[10:11]
	v_readlane_b32 s10, v0, s12
	v_cndmask_b32_e64 v35, 0, 1, s[0:1]
	v_cmp_lt_u32_e64 s[12:13], s12, v168
	v_cmp_gt_f32_e64 s[0:1], s10, v0
	v_cmp_eq_f32_e64 s[10:11], s10, v0
	s_and_b64 s[10:11], s[10:11], s[12:13]
	s_or_b64 s[0:1], s[0:1], s[10:11]
	s_add_i32 s18, s18, 4
	v_addc_co_u32_e64 v34, s[0:1], v34, v35, s[0:1]
	s_cmp_lt_u32 s18, s101
	s_cbranch_scc1 .LBB0_325
	v_cmp_gt_u32_e64 s[0:1], 16, v34
	v_cmp_le_f32_e64 s[10:11], 0, v0
	s_and_b64 s[0:1], s[0:1], s[10:11]
	v_cndmask_b32_e64 v0, 0, 1, s[0:1]
	v_cmp_ne_u32_e64 s[28:29], 0, v0
	s_and_saveexec_b64 s[0:1], s[6:7]
	v_mov_b32_e32 v0, s70
	v_mov_b64_e32 v[34:35], s[28:29]
	ds_write_b64 v0, v[34:35] offset:53280
	s_or_b64 exec, exec, s[0:1]
	ds_read_b32 v0, v206 offset:38144
	s_mov_b32 s18, 0
	v_mov_b32_e32 v34, 0
	s_waitcnt lgkmcnt(0)
	v_cndmask_b32_e32 v0, v0, v231, vcc
	v_cndmask_b32_e64 v0, v0, -1.0, s[8:9]
.LBB0_329:
	s_nop 0
	v_readlane_b32 s10, v0, s18
	v_cmp_lt_u32_e64 s[12:13], s18, v168
	s_nop 0
	v_cmp_gt_f32_e64 s[0:1], s10, v0
	v_cmp_eq_f32_e64 s[10:11], s10, v0
	s_and_b64 s[10:11], s[10:11], s[12:13]
	s_add_i32 s12, s18, 1
	s_or_b64 s[0:1], s[0:1], s[10:11]
	v_readlane_b32 s10, v0, s12
	v_cndmask_b32_e64 v35, 0, 1, s[0:1]
	v_cmp_lt_u32_e64 s[12:13], s12, v168
	v_cmp_gt_f32_e64 s[0:1], s10, v0
	v_cmp_eq_f32_e64 s[10:11], s10, v0
	s_and_b64 s[10:11], s[10:11], s[12:13]
	s_or_b64 s[0:1], s[0:1], s[10:11]
	s_add_i32 s12, s18, 2
	v_addc_co_u32_e64 v34, s[0:1], v34, v35, s[0:1]
	v_readlane_b32 s10, v0, s12
	v_cmp_lt_u32_e64 s[12:13], s12, v168
	s_nop 0
	v_cmp_gt_f32_e64 s[0:1], s10, v0
	v_cmp_eq_f32_e64 s[10:11], s10, v0
	s_and_b64 s[10:11], s[10:11], s[12:13]
	s_add_i32 s12, s18, 3
	s_or_b64 s[0:1], s[0:1], s[10:11]
	v_readlane_b32 s10, v0, s12
	v_cndmask_b32_e64 v35, 0, 1, s[0:1]
	v_cmp_lt_u32_e64 s[12:13], s12, v168
	v_cmp_gt_f32_e64 s[0:1], s10, v0
	v_cmp_eq_f32_e64 s[10:11], s10, v0
	s_and_b64 s[10:11], s[10:11], s[12:13]
	s_or_b64 s[0:1], s[0:1], s[10:11]
	s_add_i32 s18, s18, 4
	v_addc_co_u32_e64 v34, s[0:1], v34, v35, s[0:1]
	s_cmp_lt_u32 s18, s101
	s_cbranch_scc1 .LBB0_329
	v_cmp_gt_u32_e64 s[0:1], 16, v34
	v_cmp_le_f32_e64 s[10:11], 0, v0
	s_and_b64 s[0:1], s[0:1], s[10:11]
	v_cndmask_b32_e64 v0, 0, 1, s[0:1]
	v_cmp_ne_u32_e64 s[30:31], 0, v0
	s_and_saveexec_b64 s[0:1], s[6:7]
	v_mov_b32_e32 v0, s70
	v_mov_b64_e32 v[34:35], s[30:31]
	ds_write_b64 v0, v[34:35] offset:53288
	s_or_b64 exec, exec, s[0:1]
	ds_read_b32 v0, v206 offset:38400
	s_mov_b32 s18, 0
	v_mov_b32_e32 v34, 0
	s_waitcnt lgkmcnt(0)
	v_cndmask_b32_e32 v0, v0, v231, vcc
	v_cndmask_b32_e64 v0, v0, -1.0, s[8:9]
.LBB0_333:
	s_nop 0
	v_readlane_b32 s10, v0, s18
	v_cmp_lt_u32_e64 s[12:13], s18, v168
	s_nop 0
	v_cmp_gt_f32_e64 s[0:1], s10, v0
	v_cmp_eq_f32_e64 s[10:11], s10, v0
	s_and_b64 s[10:11], s[10:11], s[12:13]
	s_add_i32 s12, s18, 1
	s_or_b64 s[0:1], s[0:1], s[10:11]
	v_readlane_b32 s10, v0, s12
	v_cndmask_b32_e64 v35, 0, 1, s[0:1]
	v_cmp_lt_u32_e64 s[12:13], s12, v168
	v_cmp_gt_f32_e64 s[0:1], s10, v0
	v_cmp_eq_f32_e64 s[10:11], s10, v0
	s_and_b64 s[10:11], s[10:11], s[12:13]
	s_or_b64 s[0:1], s[0:1], s[10:11]
	s_add_i32 s12, s18, 2
	v_addc_co_u32_e64 v34, s[0:1], v34, v35, s[0:1]
	v_readlane_b32 s10, v0, s12
	v_cmp_lt_u32_e64 s[12:13], s12, v168
	s_nop 0
	v_cmp_gt_f32_e64 s[0:1], s10, v0
	v_cmp_eq_f32_e64 s[10:11], s10, v0
	s_and_b64 s[10:11], s[10:11], s[12:13]
	s_add_i32 s12, s18, 3
	s_or_b64 s[0:1], s[0:1], s[10:11]
	v_readlane_b32 s10, v0, s12
	v_cndmask_b32_e64 v35, 0, 1, s[0:1]
	v_cmp_lt_u32_e64 s[12:13], s12, v168
	v_cmp_gt_f32_e64 s[0:1], s10, v0
	v_cmp_eq_f32_e64 s[10:11], s10, v0
	s_and_b64 s[10:11], s[10:11], s[12:13]
	s_or_b64 s[0:1], s[0:1], s[10:11]
	s_add_i32 s18, s18, 4
	v_addc_co_u32_e64 v34, s[0:1], v34, v35, s[0:1]
	s_cmp_lt_u32 s18, s101
	s_cbranch_scc1 .LBB0_333
	v_cmp_gt_u32_e64 s[0:1], 16, v34
	v_cmp_le_f32_e64 s[10:11], 0, v0
	s_and_b64 s[0:1], s[0:1], s[10:11]
	v_cndmask_b32_e64 v0, 0, 1, s[0:1]
	v_cmp_ne_u32_e64 s[10:11], 0, v0
	s_and_saveexec_b64 s[0:1], s[6:7]
	v_mov_b32_e32 v0, s70
	v_mov_b64_e32 v[34:35], s[10:11]
	ds_write_b64 v0, v[34:35] offset:53296
	s_or_b64 exec, exec, s[0:1]
	ds_read_b32 v0, v206 offset:38656
	s_mov_b32 s12, 0
	v_mov_b32_e32 v34, 0
	s_waitcnt lgkmcnt(0)
	v_cndmask_b32_e32 v0, v0, v231, vcc
	v_cndmask_b32_e64 v0, v0, -1.0, s[8:9]
.LBB0_337:
	s_nop 0
	v_readlane_b32 s0, v0, s12
	v_cmp_lt_u32_e64 s[8:9], s12, v168
	s_nop 0
	v_cmp_gt_f32_e32 vcc, s0, v0
	v_cmp_eq_f32_e64 s[0:1], s0, v0
	s_and_b64 s[0:1], s[0:1], s[8:9]
	s_or_b64 s[0:1], vcc, s[0:1]
	s_add_i32 s8, s12, 1
	v_cndmask_b32_e64 v35, 0, 1, s[0:1]
	v_readlane_b32 s0, v0, s8
	v_cmp_lt_u32_e64 s[8:9], s8, v168
	s_nop 0
	v_cmp_gt_f32_e32 vcc, s0, v0
	v_cmp_eq_f32_e64 s[0:1], s0, v0
	s_and_b64 s[0:1], s[0:1], s[8:9]
	s_or_b64 vcc, vcc, s[0:1]
	s_add_i32 s8, s12, 2
	v_addc_co_u32_e32 v34, vcc, v34, v35, vcc
	v_readlane_b32 s0, v0, s8
	v_cmp_lt_u32_e64 s[8:9], s8, v168
	s_nop 0
	v_cmp_gt_f32_e32 vcc, s0, v0
	v_cmp_eq_f32_e64 s[0:1], s0, v0
	s_and_b64 s[0:1], s[0:1], s[8:9]
	s_or_b64 s[0:1], vcc, s[0:1]
	s_add_i32 s8, s12, 3
	v_cndmask_b32_e64 v35, 0, 1, s[0:1]
	v_readlane_b32 s0, v0, s8
	v_cmp_lt_u32_e64 s[8:9], s8, v168
	s_add_i32 s12, s12, 4
	v_cmp_gt_f32_e32 vcc, s0, v0
	v_cmp_eq_f32_e64 s[0:1], s0, v0
	s_and_b64 s[0:1], s[0:1], s[8:9]
	s_or_b64 vcc, vcc, s[0:1]
	v_addc_co_u32_e32 v34, vcc, v34, v35, vcc
	s_cmp_lt_u32 s12, s101
	s_cbranch_scc1 .LBB0_337
	v_cmp_gt_u32_e32 vcc, 16, v34
	v_cmp_le_f32_e64 s[0:1], 0, v0
	s_and_b64 s[0:1], vcc, s[0:1]
	s_nop 0
	v_cndmask_b32_e64 v0, 0, 1, s[0:1]
	v_cmp_ne_u32_e64 s[8:9], 0, v0
	s_and_saveexec_b64 s[0:1], s[6:7]
	v_mov_b32_e32 v0, s70
	v_mov_b64_e32 v[34:35], s[8:9]
	ds_write_b64 v0, v[34:35] offset:53304
	s_or_b64 exec, exec, s[0:1]
	s_and_saveexec_b64 s[0:1], s[6:7]
	s_cbranch_execz .LBB0_345
	s_or_b64 s[12:13], s[86:87], s[20:21]
	s_or_b64 s[12:13], s[12:13], s[24:25]
	s_or_b64 s[12:13], s[12:13], s[26:27]
	s_or_b64 s[12:13], s[12:13], s[28:29]
	s_or_b64 s[12:13], s[12:13], s[30:31]
	v_mbcnt_lo_u32_b32 v0, exec_lo, 0
	s_or_b64 s[10:11], s[12:13], s[10:11]
	v_mbcnt_hi_u32_b32 v0, exec_hi, v0
	s_or_b64 s[8:9], s[10:11], s[8:9]
	v_cmp_eq_u32_e32 vcc, 0, v0
	s_and_saveexec_b64 s[10:11], vcc
	v_mov_b32_e32 v0, s8
	ds_or_b32 v1, v0 offset:53760
	s_or_b64 exec, exec, s[10:11]
	v_mbcnt_lo_u32_b32 v0, exec_lo, 0
	v_mbcnt_hi_u32_b32 v0, exec_hi, v0
	v_cmp_eq_u32_e32 vcc, 0, v0
	s_and_b64 exec, exec, vcc
	v_mov_b32_e32 v0, s9
	ds_or_b32 v1, v0 offset:53764
